# e15: late_convert(att_w_out) in the P2 tail also loads 32-deep (on top of e14)
# speedup vs baseline: 1.0065x; 1.0065x over previous
.Le15_rd:
	s_waitcnt lgkmcnt(0)
	s_sub_i32 s6, 0, s5
	ds_read2_b32 v[6:7], v41 offset1:33
	s_add_i32 s6, s6, s10
	s_waitcnt lgkmcnt(0)
	v_cvt_pk_bf16_f32 v48, v6, v7
	ds_read2_b32 v[6:7], v41 offset0:66 offset1:99
	v_add_u32_e32 v54, s6, v40
	s_waitcnt lgkmcnt(0)
	v_cvt_pk_bf16_f32 v49, v6, v7
	ds_read2_b32 v[6:7], v41 offset0:132 offset1:165
	s_ashr_i32 s5, s4, 31
	v_ashrrev_i32_e32 v55, 31, v54
	s_waitcnt lgkmcnt(0)
	v_cvt_pk_bf16_f32 v50, v6, v7
	ds_read2_b32 v[6:7], v41 offset0:198 offset1:231
	v_lshl_add_u64 v[52:53], s[4:5], 1, v[4:5]
	v_lshlrev_b64 v[56:57], 13, v[54:55]
	s_waitcnt lgkmcnt(0)
	v_cvt_pk_bf16_f32 v51, v6, v7
	ds_read2_b32 v[6:7], v41 offset0:8 offset1:41
	v_lshl_add_u64 v[56:57], v[52:53], 0, v[56:57]
	global_store_dwordx4 v[56:57], v[48:51], off
	v_add_u32_e32 v56, 8, v54
	v_ashrrev_i32_e32 v57, 31, v56
	s_waitcnt lgkmcnt(0)
	v_cvt_pk_bf16_f32 v48, v6, v7
	ds_read2_b32 v[6:7], v41 offset0:74 offset1:107
	s_waitcnt lgkmcnt(0)
	v_cvt_pk_bf16_f32 v49, v6, v7
	ds_read2_b32 v[6:7], v41 offset0:140 offset1:173
	s_waitcnt lgkmcnt(0)
	v_cvt_pk_bf16_f32 v50, v6, v7
	ds_read2_b32 v[6:7], v41 offset0:206 offset1:239
	v_lshlrev_b64 v[56:57], 13, v[56:57]
	s_waitcnt lgkmcnt(0)
	v_cvt_pk_bf16_f32 v51, v6, v7
	ds_read2_b32 v[6:7], v41 offset0:16 offset1:49
	v_lshl_add_u64 v[56:57], v[52:53], 0, v[56:57]
	global_store_dwordx4 v[56:57], v[48:51], off
	v_add_u32_e32 v56, 16, v54
	v_ashrrev_i32_e32 v57, 31, v56
	s_waitcnt lgkmcnt(0)
	v_cvt_pk_bf16_f32 v48, v6, v7
	ds_read2_b32 v[6:7], v41 offset0:82 offset1:115
	s_waitcnt lgkmcnt(0)
	v_cvt_pk_bf16_f32 v49, v6, v7
	ds_read2_b32 v[6:7], v41 offset0:148 offset1:181
	s_waitcnt lgkmcnt(0)
	v_cvt_pk_bf16_f32 v50, v6, v7
	ds_read2_b32 v[6:7], v41 offset0:214 offset1:247
	v_lshlrev_b64 v[56:57], 13, v[56:57]
	v_add_u32_e32 v54, 24, v54
	s_waitcnt lgkmcnt(0)
	v_cvt_pk_bf16_f32 v51, v6, v7
	ds_read2_b32 v[6:7], v41 offset0:24 offset1:57
	v_lshl_add_u64 v[56:57], v[52:53], 0, v[56:57]
	v_ashrrev_i32_e32 v55, 31, v54
	global_store_dwordx4 v[56:57], v[48:51], off
	v_lshlrev_b64 v[54:55], 13, v[54:55]
	v_lshl_add_u64 v[52:53], v[52:53], 0, v[54:55]
	s_waitcnt lgkmcnt(0)
	v_cvt_pk_bf16_f32 v48, v6, v7
	ds_read2_b32 v[6:7], v41 offset0:90 offset1:123
	s_waitcnt lgkmcnt(0)
	v_cvt_pk_bf16_f32 v49, v6, v7
	ds_read2_b32 v[6:7], v41 offset0:156 offset1:189
	s_waitcnt lgkmcnt(0)
	v_cvt_pk_bf16_f32 v50, v6, v7
	ds_read2_b32 v[6:7], v41 offset0:222 offset1:255
	s_waitcnt lgkmcnt(0)
	v_cvt_pk_bf16_f32 v51, v6, v7
	global_store_dwordx4 v[52:53], v[48:51], off
	s_waitcnt lgkmcnt(0)
	s_add_i32 s0, s0, s1
	v_add_u32_e32 v40, s11, v40
	s_cmpk_lt_i32 s0, 0x2000
	v_add_u32_e32 v1, s11, v1
	s_cbranch_scc0 .LBB0_628
.LBB0_596:
	s_ashr_i32 s4, s0, 31
	s_lshr_b32 s4, s4, 25
	s_add_i32 s4, s0, s4
	s_ashr_i32 s5, s4, 7
	s_lshl_b32 s4, s5, 6
	s_lshl_b32 s5, s5, 12
	s_sub_i32 s12, s10, s5
	v_add_u32_e32 v2, s12, v1
	s_waitcnt lgkmcnt(0)
	s_lshl_b32 s6, s4, 14
	v_lshlrev_b32_e32 v196, 2, v2
	s_add_u32 s8, s64, s6
	v_lshl_add_u32 v196, v8, 14, v196
	s_addc_u32 s9, s65, 0
	v_mov_b32_e32 v197, v42
	global_load_dword v164, v196, s[8:9] nt
	v_add_u32_e32 v196, 0x8000, v196
	global_load_dword v165, v196, s[8:9] nt
	v_add_u32_e32 v196, 0x8000, v196
	global_load_dword v166, v196, s[8:9] nt
	v_add_u32_e32 v196, 0x8000, v196
	global_load_dword v167, v196, s[8:9] nt
	v_add_u32_e32 v196, 0x8000, v196
	global_load_dword v168, v196, s[8:9] nt
	v_add_u32_e32 v196, 0x8000, v196
	global_load_dword v169, v196, s[8:9] nt
	v_add_u32_e32 v196, 0x8000, v196
	global_load_dword v170, v196, s[8:9] nt
	v_add_u32_e32 v196, 0x8000, v196
	global_load_dword v171, v196, s[8:9] nt
	v_add_u32_e32 v196, 0x8000, v196
	global_load_dword v172, v196, s[8:9] nt
	v_add_u32_e32 v196, 0x8000, v196
	global_load_dword v173, v196, s[8:9] nt
	v_add_u32_e32 v196, 0x8000, v196
	global_load_dword v174, v196, s[8:9] nt
	v_add_u32_e32 v196, 0x8000, v196
	global_load_dword v175, v196, s[8:9] nt
	v_add_u32_e32 v196, 0x8000, v196
	global_load_dword v176, v196, s[8:9] nt
	v_add_u32_e32 v196, 0x8000, v196
	global_load_dword v177, v196, s[8:9] nt
	v_add_u32_e32 v196, 0x8000, v196
	global_load_dword v178, v196, s[8:9] nt
	v_add_u32_e32 v196, 0x8000, v196
	global_load_dword v179, v196, s[8:9] nt
	v_add_u32_e32 v196, 0x8000, v196
	global_load_dword v180, v196, s[8:9] nt
	v_add_u32_e32 v196, 0x8000, v196
	global_load_dword v181, v196, s[8:9] nt
	v_add_u32_e32 v196, 0x8000, v196
	global_load_dword v182, v196, s[8:9] nt
	v_add_u32_e32 v196, 0x8000, v196
	global_load_dword v183, v196, s[8:9] nt
	v_add_u32_e32 v196, 0x8000, v196
	global_load_dword v184, v196, s[8:9] nt
	v_add_u32_e32 v196, 0x8000, v196
	global_load_dword v185, v196, s[8:9] nt
	v_add_u32_e32 v196, 0x8000, v196
	global_load_dword v186, v196, s[8:9] nt
	v_add_u32_e32 v196, 0x8000, v196
	global_load_dword v187, v196, s[8:9] nt
	v_add_u32_e32 v196, 0x8000, v196
	global_load_dword v188, v196, s[8:9] nt
	v_add_u32_e32 v196, 0x8000, v196
	global_load_dword v189, v196, s[8:9] nt
	v_add_u32_e32 v196, 0x8000, v196
	global_load_dword v190, v196, s[8:9] nt
	v_add_u32_e32 v196, 0x8000, v196
	global_load_dword v191, v196, s[8:9] nt
	v_add_u32_e32 v196, 0x8000, v196
	global_load_dword v192, v196, s[8:9] nt
	v_add_u32_e32 v196, 0x8000, v196
	global_load_dword v193, v196, s[8:9] nt
	v_add_u32_e32 v196, 0x8000, v196
	global_load_dword v194, v196, s[8:9] nt
	v_add_u32_e32 v196, 0x8000, v196
	global_load_dword v195, v196, s[8:9] nt
	s_waitcnt vmcnt(30)
	ds_write2_b32 v197, v164, v165 offset1:66
	s_waitcnt vmcnt(28)
	ds_write2_b32 v197, v166, v167 offset0:132 offset1:198
	v_add_u32_e32 v197, 0x420, v197
	s_waitcnt vmcnt(26)
	ds_write2_b32 v197, v168, v169 offset1:66
	s_waitcnt vmcnt(24)
	ds_write2_b32 v197, v170, v171 offset0:132 offset1:198
	v_add_u32_e32 v197, 0x420, v197
	s_waitcnt vmcnt(22)
	ds_write2_b32 v197, v172, v173 offset1:66
	s_waitcnt vmcnt(20)
	ds_write2_b32 v197, v174, v175 offset0:132 offset1:198
	v_add_u32_e32 v197, 0x420, v197
	s_waitcnt vmcnt(18)
	ds_write2_b32 v197, v176, v177 offset1:66
	s_waitcnt vmcnt(16)
	ds_write2_b32 v197, v178, v179 offset0:132 offset1:198
	v_add_u32_e32 v197, 0x420, v197
	s_waitcnt lgkmcnt(0)
	s_waitcnt vmcnt(14)
	ds_write2_b32 v197, v180, v181 offset1:66
	s_waitcnt vmcnt(12)
	ds_write2_b32 v197, v182, v183 offset0:132 offset1:198
	v_add_u32_e32 v197, 0x420, v197
	s_waitcnt vmcnt(10)
	ds_write2_b32 v197, v184, v185 offset1:66
	s_waitcnt vmcnt(8)
	ds_write2_b32 v197, v186, v187 offset0:132 offset1:198
	v_add_u32_e32 v197, 0x420, v197
	s_waitcnt vmcnt(6)
	ds_write2_b32 v197, v188, v189 offset1:66
	s_waitcnt vmcnt(4)
	ds_write2_b32 v197, v190, v191 offset0:132 offset1:198
	v_add_u32_e32 v197, 0x420, v197
	s_waitcnt vmcnt(2)
	ds_write2_b32 v197, v192, v193 offset1:66
	s_waitcnt vmcnt(0)
	ds_write2_b32 v197, v194, v195 offset0:132 offset1:198
	s_branch .Le15_rd
